# speedup vs baseline: 1.0559x; 1.0114x over previous
; DEV void cmp2_item(const Params& p, int l, int it, char* lds) {
;     ...
;     const float* w2 = (kv ? p.c_v2 : p.c_k2) + (size_t)l * 256 * 128;
;     const int d = tid & 127, half = tid >> 7;
;     float acc[8];
; #pragma unroll
;     for (int rr = 0; rr < 8; ++rr) acc[rr] = 0.f;
; #pragma unroll 8
;     for (int j = half * 128; j < half * 128 + 128; ++j) {
;       const float w = w2[j * 128 + d];
;       const float4 h0 = *(const float4*)(hsT + j * 8), h1 = *(const float4*)(hsT + j * 8 + 4);
;       acc[0] += h0.x * w; acc[1] += h0.y * w; acc[2] += h0.z * w; acc[3] += h0.w * w;
;       acc[4] += h1.x * w; acc[5] += h1.y * w; acc[6] += h1.z * w; acc[7] += h1.w * w;
;     }
.LBB0_440:
	v_add_u32_e32 v242, 0xfffffe00, v44
	v_ashrrev_i32_e32 v243, 31, v242
	v_lshl_add_u64 v[242:243], v[242:243], 2, s[8:9]
	global_load_dword v246, v[242:243], off
	v_add_u32_e32 v242, 0xfffffe80, v44
	v_ashrrev_i32_e32 v243, 31, v242
	v_lshl_add_u64 v[242:243], v[242:243], 2, s[8:9]
	global_load_dword v247, v[242:243], off
	v_add_u32_e32 v242, 0xffffff00, v44
	v_ashrrev_i32_e32 v243, 31, v242
	v_lshl_add_u64 v[242:243], v[242:243], 2, s[8:9]
	global_load_dword v248, v[242:243], off
	v_add_u32_e32 v242, 0xffffff80, v44
	v_ashrrev_i32_e32 v243, 31, v242
	v_lshl_add_u64 v[242:243], v[242:243], 2, s[8:9]
	global_load_dword v249, v[242:243], off
	v_mov_b32_e32 v242, v44
	v_ashrrev_i32_e32 v243, 31, v242
	v_lshl_add_u64 v[242:243], v[242:243], 2, s[8:9]
	global_load_dword v250, v[242:243], off
	v_add_u32_e32 v242, 0x80, v44
	v_ashrrev_i32_e32 v243, 31, v242
	v_lshl_add_u64 v[242:243], v[242:243], 2, s[8:9]
	global_load_dword v251, v[242:243], off
	v_add_u32_e32 v242, 0x100, v44
	v_ashrrev_i32_e32 v243, 31, v242
	v_lshl_add_u64 v[242:243], v[242:243], 2, s[8:9]
	global_load_dword v252, v[242:243], off
	v_add_u32_e32 v242, 0x180, v44
	v_ashrrev_i32_e32 v243, 31, v242
	v_lshl_add_u64 v[242:243], v[242:243], 2, s[8:9]
	global_load_dword v253, v[242:243], off
	v_add_u32_e32 v6, 0xfffffe00, v44
	v_ashrrev_i32_e32 v7, 31, v6
	v_lshl_add_u64 v[6:7], v[6:7], 2, s[8:9]
	s_nop 0
	ds_read_b128 v[6:9], v70
	ds_read_b128 v[14:17], v70 offset:16
	v_add_u32_e32 v10, -2, v71
	s_andn2_b64 s[94:95], s[94:95], exec
	s_andn2_b64 s[30:31], s[30:31], exec
	s_andn2_b64 s[92:93], s[92:93], exec
	s_andn2_b64 s[90:91], s[90:91], exec
	s_andn2_b64 s[86:87], s[86:87], exec
	s_andn2_b64 s[82:83], s[82:83], exec
	s_or_b64 s[78:79], s[78:79], exec
	v_cmp_lt_i32_e32 vcc, v10, v3
	s_or_b64 s[80:81], s[80:81], exec
	s_waitcnt vmcnt(0) lgkmcnt(1)
	v_mov_b32_e32 v18, v246
	v_pk_fma_f32 v[12:13], v[18:19], v[6:7], v[4:5] op_sel_hi:[0,1,1]
	v_pk_fma_f32 v[10:11], v[18:19], v[8:9], v[32:33] op_sel_hi:[0,1,1]
	s_waitcnt lgkmcnt(0)
	v_pk_fma_f32 v[8:9], v[18:19], v[14:15], v[28:29] op_sel_hi:[0,1,1]
	v_pk_fma_f32 v[6:7], v[18:19], v[16:17], v[22:23] op_sel_hi:[0,1,1]
	s_and_saveexec_b64 s[22:23], vcc
	s_cbranch_execz .LBB0_439
	v_add_u32_e32 v4, 0xfffffe80, v44
	v_ashrrev_i32_e32 v5, 31, v4
	v_lshl_add_u64 v[4:5], v[4:5], 2, s[8:9]
	v_mov_b32_e32 v4, v247
	ds_read_b128 v[14:17], v70 offset:32
	ds_read_b128 v[18:21], v70 offset:48
	v_add_u32_e32 v5, -1, v71
	s_mov_b64 s[6:7], -1
	s_mov_b64 s[26:27], 0
	s_mov_b64 s[84:85], -1
	s_mov_b64 s[76:77], 0
	s_mov_b64 s[52:53], 0
	s_mov_b64 s[54:55], 0
	v_cmp_lt_i32_e32 vcc, v5, v3
	s_mov_b64 s[56:57], 0
	s_waitcnt vmcnt(0) lgkmcnt(1)
	v_pk_fma_f32 v[14:15], v[4:5], v[14:15], v[12:13] op_sel_hi:[0,1,1]
	v_pk_fma_f32 v[16:17], v[4:5], v[16:17], v[10:11] op_sel_hi:[0,1,1]
	s_waitcnt lgkmcnt(0)
	v_pk_fma_f32 v[18:19], v[4:5], v[18:19], v[8:9] op_sel_hi:[0,1,1]
	v_pk_fma_f32 v[20:21], v[4:5], v[20:21], v[6:7] op_sel_hi:[0,1,1]
	s_and_saveexec_b64 s[74:75], vcc
	s_cbranch_execz .LBB0_438
	v_add_u32_e32 v4, 0xffffff00, v44
	v_ashrrev_i32_e32 v5, 31, v4
	v_lshl_add_u64 v[4:5], v[4:5], 2, s[8:9]
	v_mov_b32_e32 v4, v248
	ds_read_b128 v[24:27], v70 offset:64
	ds_read_b128 v[30:33], v70 offset:80
	v_cmp_lt_i32_e32 vcc, v71, v3
	s_mov_b64 s[58:59], -1
	s_mov_b64 s[60:61], -1
	s_waitcnt vmcnt(0) lgkmcnt(1)
	v_pk_fma_f32 v[24:25], v[4:5], v[24:25], v[14:15] op_sel_hi:[0,1,1]
	v_pk_fma_f32 v[26:27], v[4:5], v[26:27], v[16:17] op_sel_hi:[0,1,1]
	s_waitcnt lgkmcnt(0)
	v_pk_fma_f32 v[30:31], v[4:5], v[30:31], v[18:19] op_sel_hi:[0,1,1]
	v_pk_fma_f32 v[34:35], v[4:5], v[32:33], v[20:21] op_sel_hi:[0,1,1]
	s_and_saveexec_b64 s[6:7], vcc
	s_cbranch_execz .LBB0_437
; DEV void cmp2_item(const Params& p, int l, int it, char* lds) {
;     ...
;     const float* w2 = (kv ? p.c_v2 : p.c_k2) + (size_t)l * 256 * 128;
;     const int d = tid & 127, half = tid >> 7;
;     float acc[8];
; #pragma unroll
;     for (int rr = 0; rr < 8; ++rr) acc[rr] = 0.f;
; #pragma unroll 8
;     for (int j = half * 128; j < half * 128 + 128; ++j) {
;       const float w = w2[j * 128 + d];
;       const float4 h0 = *(const float4*)(hsT + j * 8), h1 = *(const float4*)(hsT + j * 8 + 4);
;       acc[0] += h0.x * w; acc[1] += h0.y * w; acc[2] += h0.z * w; acc[3] += h0.w * w;
;       acc[4] += h1.x * w; acc[5] += h1.y * w; acc[6] += h1.z * w; acc[7] += h1.w * w;
;     }
	v_add_u32_e32 v4, 0xffffff80, v44
	v_ashrrev_i32_e32 v5, 31, v4
	v_lshl_add_u64 v[4:5], v[4:5], 2, s[8:9]
	v_mov_b32_e32 v4, v249
	ds_read_b128 v[36:39], v70 offset:96
	ds_read_b128 v[40:43], v70 offset:112
	v_add_u32_e32 v5, 1, v71
	v_cmp_lt_i32_e32 vcc, v5, v3
	s_waitcnt vmcnt(0) lgkmcnt(1)
	v_pk_fma_f32 v[36:37], v[4:5], v[36:37], v[24:25] op_sel_hi:[0,1,1]
	v_pk_fma_f32 v[38:39], v[4:5], v[38:39], v[26:27] op_sel_hi:[0,1,1]
	s_waitcnt lgkmcnt(0)
	v_pk_fma_f32 v[40:41], v[4:5], v[40:41], v[30:31] op_sel_hi:[0,1,1]
	v_pk_fma_f32 v[42:43], v[4:5], v[42:43], v[34:35] op_sel_hi:[0,1,1]
	s_and_saveexec_b64 s[26:27], vcc
	s_cbranch_execz .LBB0_436
	v_ashrrev_i32_e32 v45, 31, v44
	v_lshl_add_u64 v[4:5], v[44:45], 2, s[8:9]
	v_mov_b32_e32 v4, v250
	ds_read_b128 v[46:49], v70 offset:128
	ds_read_b128 v[50:53], v70 offset:144
	v_add_u32_e32 v5, 2, v71
	v_cmp_lt_i32_e32 vcc, v5, v3
	s_waitcnt vmcnt(0) lgkmcnt(1)
	v_pk_fma_f32 v[46:47], v[4:5], v[46:47], v[36:37] op_sel_hi:[0,1,1]
	v_pk_fma_f32 v[48:49], v[4:5], v[48:49], v[38:39] op_sel_hi:[0,1,1]
	s_waitcnt lgkmcnt(0)
	v_pk_fma_f32 v[50:51], v[4:5], v[50:51], v[40:41] op_sel_hi:[0,1,1]
	v_pk_fma_f32 v[52:53], v[4:5], v[52:53], v[42:43] op_sel_hi:[0,1,1]
	s_and_saveexec_b64 s[84:85], vcc
	s_cbranch_execz .LBB0_435
	v_add_u32_e32 v4, 0x80, v44
	v_ashrrev_i32_e32 v5, 31, v4
	v_lshl_add_u64 v[4:5], v[4:5], 2, s[8:9]
	v_mov_b32_e32 v4, v251
	ds_read_b128 v[54:57], v70 offset:160
	ds_read_b128 v[58:61], v70 offset:176
	v_add_u32_e32 v5, 3, v71
	s_mov_b64 s[56:57], -1
	v_cmp_lt_i32_e32 vcc, v5, v3
	s_waitcnt vmcnt(0) lgkmcnt(1)
	v_pk_fma_f32 v[54:55], v[4:5], v[54:55], v[46:47] op_sel_hi:[0,1,1]
	v_pk_fma_f32 v[56:57], v[4:5], v[56:57], v[48:49] op_sel_hi:[0,1,1]
	s_waitcnt lgkmcnt(0)
	v_pk_fma_f32 v[58:59], v[4:5], v[58:59], v[50:51] op_sel_hi:[0,1,1]
	v_pk_fma_f32 v[60:61], v[4:5], v[60:61], v[52:53] op_sel_hi:[0,1,1]
	s_and_saveexec_b64 s[76:77], vcc
	s_cbranch_execz .LBB0_434
	v_add_u32_e32 v4, 0x100, v44
	v_ashrrev_i32_e32 v5, 31, v4
	v_lshl_add_u64 v[4:5], v[4:5], 2, s[8:9]
	v_mov_b32_e32 v4, v252
	ds_read_b128 v[62:65], v70 offset:192
	ds_read_b128 v[66:69], v70 offset:208
	v_add_u32_e32 v5, 4, v71
	s_mov_b64 s[54:55], -1
	v_cmp_lt_i32_e32 vcc, v5, v3
	s_waitcnt vmcnt(0) lgkmcnt(1)
	v_pk_fma_f32 v[62:63], v[4:5], v[62:63], v[54:55] op_sel_hi:[0,1,1]
	v_pk_fma_f32 v[64:65], v[4:5], v[64:65], v[56:57] op_sel_hi:[0,1,1]
	s_waitcnt lgkmcnt(0)
	v_pk_fma_f32 v[66:67], v[4:5], v[66:67], v[58:59] op_sel_hi:[0,1,1]
	v_pk_fma_f32 v[68:69], v[4:5], v[68:69], v[60:61] op_sel_hi:[0,1,1]
	s_and_saveexec_b64 s[52:53], vcc
	s_cbranch_execz .LBB0_433
	v_add_u32_e32 v4, 0x180, v44
	v_ashrrev_i32_e32 v5, 31, v4
	v_lshl_add_u64 v[4:5], v[4:5], 2, s[8:9]
	v_mov_b32_e32 v4, v253
	ds_read_b128 v[72:75], v70 offset:224
	ds_read_b128 v[76:79], v70 offset:240
	v_add_u32_e32 v5, 5, v71
	v_add_u32_e32 v45, 8, v71
	v_cmp_ge_i32_e32 vcc, v5, v3
	v_add_u32_e32 v70, 0x100, v70
	v_add_u32_e32 v44, 0x400, v44
	s_xor_b64 s[56:57], exec, -1
	s_orn2_b64 s[54:55], vcc, exec
	v_mov_b32_e32 v71, v45
	s_waitcnt vmcnt(0) lgkmcnt(0)
	v_pk_fma_f32 v[22:23], v[4:5], v[78:79], v[68:69] op_sel_hi:[0,1,1]
	v_pk_fma_f32 v[28:29], v[4:5], v[76:77], v[66:67] op_sel_hi:[0,1,1]
	v_pk_fma_f32 v[32:33], v[4:5], v[74:75], v[64:65] op_sel_hi:[0,1,1]
	v_pk_fma_f32 v[4:5], v[4:5], v[72:73], v[62:63] op_sel_hi:[0,1,1]
	s_branch .LBB0_433
